# gemm prologue: second staging batch issued before waiting on the first (vmcnt 2 to 8)
# baseline (speedup 1.0000x reference)
; #define PG8_STAGE(bufoff, gbase, voff) do { _Pragma("unroll") for (int _i = 0; _i < 2; ++_i) \
;         __builtin_amdgcn_global_load_lds((const unsigned*)((const char*)(gbase) + (voff)[_i]), (PG8_LAS unsigned*)(lds + (bufoff) + ldsw + _i * 8192), 16, 0, 0); } while (0)
; #define PG8_WAIT_V(n) asm volatile("s_waitcnt vmcnt(" #n ")" ::: "memory")
; #define PG8_BAR __builtin_amdgcn_s_barrier()
; template <class Epi, class Sched, bool ALIGN_EPI = false, bool SP2 = false>
; __device__ __forceinline__ void gemm_phase(PG8_LAS unsigned char* lds, const Gemm g, const Sched& S, const Epi& E, int tid_in) {
;     ...
;     const int aoff = lds_byte(wr * 64 + fr, fq * 8), boff = lds_byte(wc * 32 + fr, fq * 8);
;     ...
;         PG8_STAGE(PG8_SB(0, 0), cB, voffB); PG8_STAGE(PG8_SB(0, 1), cB + hstep, voffB); PG8_STAGE(PG8_SA(0, 0), cA, voffA); PG8_STAGE(PG8_SA(0, 1), cA + hstep, voffA);
;         if (wr == 1) PG8_BAR;
;         PG8_WAIT_V(2); PG8_BAR;
;         PG8_STAGE(PG8_SB(1, 0), cB + kstep, voffB); PG8_STAGE(PG8_SA(1, 0), cA + kstep, voffA); PG8_STAGE(PG8_SB(1, 1), cB + hstep + kstep, voffB);
;         PG8_WAIT_V(6); PG8_BAR;
.LBB0_181:
	s_add_u32 s36, s22, 0xb400000
	s_addc_u32 s37, s23, 0
	s_lshl_b32 s39, s39, 5
	s_and_b32 s68, s39, 0x60
	s_add_i32 m0, s61, 0x18000
	v_lshl_add_u64 v[8:9], v[8:9], 0, s[26:27]
	s_lshl_b32 s65, s40, 6
	s_lshl_b32 s42, s40, 13
	s_lshl_b32 s39, s68, 7
	global_load_lds_dwordx4 v[8:9], off
	v_lshl_add_u64 v[6:7], v[6:7], 0, s[26:27]
	s_add_i32 m0, s61, 0x1a000
	s_add_i32 s69, s61, 0x8000
	s_add_i32 s70, s61, 0xa000
	global_load_lds_dwordx4 v[6:7], off
	v_lshl_add_u64 v[2:3], v[2:3], 0, s[26:27]
	s_mov_b32 m0, s69
	s_add_u32 s40, s52, 0x40080
	global_load_lds_dwordx4 v[2:3], off
	v_lshl_add_u64 v[2:3], v[4:5], 0, s[26:27]
	s_mov_b32 m0, s70
	s_addc_u32 s41, s53, 0
	global_load_lds_dwordx4 v[2:3], off
	s_add_i32 m0, s61, 0x1c000
	v_lshl_add_u64 v[2:3], s[40:41], 0, v[0:1]
	global_load_lds_dwordx4 v[2:3], off
	v_lshl_add_u64 v[2:3], s[40:41], 0, v[132:133]
	s_add_i32 m0, s61, 0x1e000
	v_bfe_u32 v146, v11, 4, 2
	global_load_lds_dwordx4 v[2:3], off
	v_and_b32_e32 v131, 15, v11
	v_lshlrev_b32_e32 v2, 4, v146
	v_lshlrev_b32_e32 v3, 2, v11
	v_lshl_or_b32 v2, v131, 6, v2
	v_and_b32_e32 v3, 32, v3
	v_bitop3_b32 v4, v2, s42, v3 bitop3:0xde
	v_bitop3_b32 v147, v2, s39, v3 bitop3:0xde
	v_lshlrev_b32_e32 v2, 14, v15
	v_and_b32_e32 v2, 0xffff8000, v2
	v_lshl_add_u32 v2, v14, 11, v2
	v_and_b32_e32 v3, 1, v15
	v_lshl_or_b32 v2, v3, 6, v2
	v_lshl_add_u32 v138, v16, 1, v2
	v_lshlrev_b32_e32 v2, 14, v10
	v_and_b32_e32 v2, 0xffff8000, v2
	s_waitcnt vmcnt(8)
	s_barrier
	s_waitcnt vmcnt(6)
	v_lshl_add_u32 v2, v12, 11, v2
	v_and_b32_e32 v3, 1, v10
	s_cmpk_lt_u32 s38, 0x100
	v_lshl_or_b32 v2, v3, 6, v2
	v_readlane_b32 s40, v253, 24
	s_cselect_b64 s[38:39], -1, 0
	v_mov_b32_e32 v139, v1
	v_lshl_add_u32 v140, v13, 1, v2
	v_mov_b32_e32 v141, v1
	s_mov_b32 s76, 0
	v_add_u32_e32 v148, 0, v4
	v_readlane_b32 s78, v255, 11
	s_mov_b32 s77, s40
	s_mov_b32 s74, 0
	s_barrier
	v_readlane_b32 s41, v253, 25
	s_branch .LBB0_184

; #define PG8_STAGE(bufoff, gbase, voff) do { _Pragma("unroll") for (int _i = 0; _i < 2; ++_i) \
;         __builtin_amdgcn_global_load_lds((const unsigned*)((const char*)(gbase) + (voff)[_i]), (PG8_LAS unsigned*)(lds + (bufoff) + ldsw + _i * 8192), 16, 0, 0); } while (0)
; #define PG8_WAIT_V(n) asm volatile("s_waitcnt vmcnt(" #n ")" ::: "memory")
; #define PG8_BAR __builtin_amdgcn_s_barrier()
; template <class Epi, class Sched, bool ALIGN_EPI = false, bool SP2 = false>
; __device__ __forceinline__ void gemm_phase(PG8_LAS unsigned char* lds, const Gemm g, const Sched& S, const Epi& E, int tid_in) {
;     ...
;     const int aoff = lds_byte(wr * 64 + fr, fq * 8), boff = lds_byte(wc * 32 + fr, fq * 8);
;     ...
;         PG8_STAGE(PG8_SB(0, 0), cB, voffB); PG8_STAGE(PG8_SB(0, 1), cB + hstep, voffB); PG8_STAGE(PG8_SA(0, 0), cA, voffA); PG8_STAGE(PG8_SA(0, 1), cA + hstep, voffA);
;         if (wr == 1) PG8_BAR;
;         PG8_WAIT_V(2); PG8_BAR;
;         PG8_STAGE(PG8_SB(1, 0), cB + kstep, voffB); PG8_STAGE(PG8_SA(1, 0), cA + kstep, voffA); PG8_STAGE(PG8_SB(1, 1), cB + hstep + kstep, voffB);
;         PG8_WAIT_V(6); PG8_BAR;
.LBB0_200:
	s_add_u32 s22, s22, 0x1b400000
	s_addc_u32 s23, s23, 0
	v_bfe_u32 v161, v130, 4, 2
	s_lshl_b32 s37, s37, 5
	v_and_b32_e32 v160, 15, v130
	v_lshlrev_b32_e32 v12, 4, v161
	v_lshlrev_b32_e32 v13, 2, v130
	s_and_b32 s69, s37, 0x60
	s_add_i32 m0, s62, 0x18000
	v_lshl_add_u64 v[2:3], v[2:3], 0, s[26:27]
	s_lshl_b32 s68, s40, 6
	v_lshl_or_b32 v12, v160, 6, v12
	s_lshl_b32 s40, s40, 13
	v_and_b32_e32 v13, 32, v13
	s_lshl_b32 s37, s69, 7
	global_load_lds_dwordx4 v[2:3], off
	s_add_i32 m0, s62, 0x1a000
	v_bitop3_b32 v14, v12, s40, v13 bitop3:0xde
	s_add_u32 s40, s33, 0x400080
	v_mov_b32_e32 v151, v1
	v_lshl_add_u64 v[2:3], v[4:5], 0, s[26:27]
	s_addc_u32 s41, s56, 0
	s_add_i32 s70, s62, 0x8000
	v_mov_b32_e32 v149, v1
	global_load_lds_dwordx4 v[2:3], off
	v_lshl_add_u64 v[2:3], s[40:41], 0, v[150:151]
	s_mov_b32 m0, s70
	s_add_i32 s75, s62, 0xa000
	global_load_lds_dwordx4 v[2:3], off
	v_lshl_add_u64 v[2:3], s[40:41], 0, v[148:149]
	s_add_u32 s40, s54, 0x40080
	s_mov_b32 m0, s75
	s_addc_u32 s41, s55, 0
	global_load_lds_dwordx4 v[2:3], off
	s_add_i32 m0, s62, 0x1c000
	v_lshl_add_u64 v[2:3], s[40:41], 0, v[0:1]
	global_load_lds_dwordx4 v[2:3], off
	v_lshl_add_u64 v[2:3], s[40:41], 0, v[146:147]
	s_add_i32 m0, s62, 0x1e000
	s_cmpk_lt_u32 s36, 0x100
	global_load_lds_dwordx4 v[2:3], off
	v_lshlrev_b32_e32 v2, 14, v10
	v_and_b32_e32 v2, 0xffff8000, v2
	v_lshl_add_u32 v2, v9, 11, v2
	v_and_b32_e32 v3, 1, v10
	v_lshl_or_b32 v2, v3, 6, v2
	v_lshl_add_u32 v152, v11, 1, v2
	v_lshlrev_b32_e32 v2, 14, v6
	v_and_b32_e32 v2, 0xffff8000, v2
	s_waitcnt vmcnt(8)
	s_barrier
	s_waitcnt vmcnt(6)
	v_lshl_add_u32 v2, v7, 11, v2
	v_and_b32_e32 v3, 1, v6
	v_lshl_or_b32 v2, v3, 6, v2
	v_bitop3_b32 v162, v12, s37, v13 bitop3:0xde
	s_cselect_b64 s[40:41], -1, 0
	v_mov_b32_e32 v153, v1
	v_lshl_add_u32 v154, v8, 1, v2
	v_mov_b32_e32 v155, v1
	s_mov_b64 s[52:53], -1
	s_mov_b32 s51, 0
	v_add_u32_e32 v163, 0, v14
	s_mov_b64 s[56:57], s[28:29]
	s_barrier
	s_branch .LBB0_203

; #define PG8_STAGE(bufoff, gbase, voff) do { _Pragma("unroll") for (int _i = 0; _i < 2; ++_i) \
;         __builtin_amdgcn_global_load_lds((const unsigned*)((const char*)(gbase) + (voff)[_i]), (PG8_LAS unsigned*)(lds + (bufoff) + ldsw + _i * 8192), 16, 0, 0); } while (0)
; #define PG8_WAIT_V(n) asm volatile("s_waitcnt vmcnt(" #n ")" ::: "memory")
; #define PG8_BAR __builtin_amdgcn_s_barrier()
; template <class Epi, class Sched, bool ALIGN_EPI = false, bool SP2 = false>
; __device__ __forceinline__ void gemm_phase(PG8_LAS unsigned char* lds, const Gemm g, const Sched& S, const Epi& E, int tid_in) {
;     ...
;     const int aoff = lds_byte(wr * 64 + fr, fq * 8), boff = lds_byte(wc * 32 + fr, fq * 8);
;     ...
;         PG8_STAGE(PG8_SB(0, 0), cB, voffB); PG8_STAGE(PG8_SB(0, 1), cB + hstep, voffB); PG8_STAGE(PG8_SA(0, 0), cA, voffA); PG8_STAGE(PG8_SA(0, 1), cA + hstep, voffA);
;         if (wr == 1) PG8_BAR;
;         PG8_WAIT_V(2); PG8_BAR;
;         PG8_STAGE(PG8_SB(1, 0), cB + kstep, voffB); PG8_STAGE(PG8_SA(1, 0), cA + kstep, voffA); PG8_STAGE(PG8_SB(1, 1), cB + hstep + kstep, voffB);
;         PG8_WAIT_V(6); PG8_BAR;
.LBB0_349:
	v_readlane_b32 s40, v253, 8
	s_and_b64 s[28:29], s[92:93], exec
	v_readlane_b32 s41, v253, 9
	s_cselect_b32 s29, s41, 0
	s_cselect_b32 s28, s40, 0
	s_add_u32 s40, s56, 0x3400000
	v_readlane_b32 s42, v253, 10
	s_addc_u32 s41, s57, 0
	v_readlane_b32 s43, v253, 11
	s_add_u32 s42, s56, 0x3000000
	v_bfe_u32 v193, v10, 4, 2
	s_addc_u32 s43, s57, 0
	s_and_b32 s87, s36, 3
	v_and_b32_e32 v195, 15, v10
	v_lshlrev_b32_e32 v17, 4, v193
	v_lshlrev_b32_e32 v10, 2, v10
	s_lshl_b32 s36, s37, 6
	v_lshl_or_b32 v17, v195, 6, v17
	s_lshl_b32 s37, s37, 13
	v_and_b32_e32 v10, 32, v10
	s_lshl_b32 s38, s87, 12
	s_add_i32 m0, s76, 0x18000
	v_lshl_add_u64 v[8:9], v[8:9], 0, s[26:27]
	v_readlane_b32 s46, v253, 14
	v_bitop3_b32 v18, v17, s37, v10 bitop3:0xde
	s_lshl_b32 s37, s87, 5
	v_bitop3_b32 v214, v17, s38, v10 bitop3:0xde
	global_load_lds_dwordx4 v[8:9], off
	v_lshl_add_u64 v[6:7], v[6:7], 0, s[26:27]
	s_add_i32 m0, s76, 0x1a000
	s_add_i32 s38, s76, 0x8000
	s_add_i32 s39, s76, 0xa000
	v_readlane_b32 s47, v253, 15
	global_load_lds_dwordx4 v[6:7], off
	v_lshl_add_u64 v[2:3], v[2:3], 0, s[26:27]
	s_mov_b32 m0, s38
	s_add_u32 s46, s60, 0x40080
	global_load_lds_dwordx4 v[2:3], off
	v_lshl_add_u64 v[2:3], v[4:5], 0, s[26:27]
	s_mov_b32 m0, s39
	s_addc_u32 s47, s61, 0
	global_load_lds_dwordx4 v[2:3], off
	s_add_i32 m0, s76, 0x1c000
	v_lshl_add_u64 v[2:3], s[46:47], 0, v[0:1]
	global_load_lds_dwordx4 v[2:3], off
	v_lshl_add_u64 v[2:3], s[46:47], 0, v[196:197]
	s_add_i32 m0, s76, 0x1e000
	v_readlane_b32 s44, v253, 12
	global_load_lds_dwordx4 v[2:3], off
	v_lshlrev_b32_e32 v2, 14, v15
	v_and_b32_e32 v2, 0xffff8000, v2
	v_lshl_add_u32 v2, v14, 11, v2
	v_and_b32_e32 v3, 1, v15
	v_lshl_or_b32 v2, v3, 6, v2
	v_lshl_add_u32 v202, v16, 1, v2
	v_lshlrev_b32_e32 v2, 14, v11
	v_and_b32_e32 v2, 0xffff8000, v2
	v_readlane_b32 s45, v253, 13
	v_readlane_b32 s48, v253, 16
	v_readlane_b32 s49, v253, 17
	s_waitcnt vmcnt(8)
	s_barrier
	s_waitcnt vmcnt(6)
	s_cmpk_lt_u32 s70, 0x100
	v_lshl_add_u32 v2, v12, 11, v2
	v_and_b32_e32 v3, 1, v11
	s_cselect_b64 s[44:45], -1, 0
	s_cmp_lg_u64 s[28:29], 0
	v_lshl_or_b32 v2, v3, 6, v2
	v_readlane_b32 s48, v254, 49
	s_mov_b32 s86, 0
	v_readlane_b32 s50, v253, 18
	v_readlane_b32 s52, v253, 20
	s_cselect_b64 s[46:47], -1, 0
	v_mov_b32_e32 v203, v1
	v_lshl_add_u32 v204, v13, 1, v2
	v_mov_b32_e32 v205, v1
	v_add_u32_e32 v215, 0, v18
	v_readlane_b32 s80, v254, 51
	s_mov_b32 s70, s48
	v_readlane_b32 s51, v253, 19
	v_readlane_b32 s53, v253, 21
	v_readlane_b32 s54, v253, 22
	v_readlane_b32 s55, v253, 23
	s_barrier
	v_readlane_b32 s49, v254, 50
	s_branch .LBB0_352

; #define PG8_STAGE(bufoff, gbase, voff) do { _Pragma("unroll") for (int _i = 0; _i < 2; ++_i) \
;         __builtin_amdgcn_global_load_lds((const unsigned*)((const char*)(gbase) + (voff)[_i]), (PG8_LAS unsigned*)(lds + (bufoff) + ldsw + _i * 8192), 16, 0, 0); } while (0)
; #define PG8_WAIT_V(n) asm volatile("s_waitcnt vmcnt(" #n ")" ::: "memory")
; #define PG8_BAR __builtin_amdgcn_s_barrier()
; template <class Epi, class Sched, bool ALIGN_EPI = false, bool SP2 = false>
; __device__ __forceinline__ void gemm_phase(PG8_LAS unsigned char* lds, const Gemm g, const Sched& S, const Epi& E, int tid_in) {
;     ...
;     const int aoff = lds_byte(wr * 64 + fr, fq * 8), boff = lds_byte(wc * 32 + fr, fq * 8);
;     ...
;         PG8_STAGE(PG8_SB(0, 0), cB, voffB); PG8_STAGE(PG8_SB(0, 1), cB + hstep, voffB); PG8_STAGE(PG8_SA(0, 0), cA, voffA); PG8_STAGE(PG8_SA(0, 1), cA + hstep, voffA);
;         if (wr == 1) PG8_BAR;
;         PG8_WAIT_V(2); PG8_BAR;
;         PG8_STAGE(PG8_SB(1, 0), cB + kstep, voffB); PG8_STAGE(PG8_SA(1, 0), cA + kstep, voffA); PG8_STAGE(PG8_SB(1, 1), cB + hstep + kstep, voffB);
;         PG8_WAIT_V(6); PG8_BAR;
.LBB0_482:
	s_add_u32 s28, s28, 0xb400000
	s_addc_u32 s29, s29, 0
	v_bfe_u32 v145, v12, 4, 2
	s_lshl_b32 s41, s41, 5
	v_and_b32_e32 v144, 15, v12
	v_lshlrev_b32_e32 v17, 4, v145
	v_lshlrev_b32_e32 v12, 2, v12
	s_and_b32 s64, s41, 0x60
	s_add_i32 m0, s59, 0x18000
	v_lshl_add_u64 v[8:9], v[8:9], 0, s[26:27]
	s_lshl_b32 s63, s42, 6
	v_lshl_or_b32 v17, v144, 6, v17
	s_lshl_b32 s42, s42, 13
	v_and_b32_e32 v12, 32, v12
	s_lshl_b32 s41, s64, 7
	global_load_lds_dwordx4 v[8:9], off
	v_lshl_add_u64 v[6:7], v[6:7], 0, s[26:27]
	s_add_i32 m0, s59, 0x1a000
	s_add_i32 s65, s59, 0x8000
	s_add_i32 s68, s59, 0xa000
	v_bitop3_b32 v18, v17, s42, v12 bitop3:0xde
	global_load_lds_dwordx4 v[6:7], off
	v_lshl_add_u64 v[2:3], v[2:3], 0, s[26:27]
	s_mov_b32 m0, s65
	s_add_u32 s42, s54, 0x40080
	global_load_lds_dwordx4 v[2:3], off
	v_lshl_add_u64 v[2:3], v[4:5], 0, s[26:27]
	s_mov_b32 m0, s68
	s_addc_u32 s43, s55, 0
	global_load_lds_dwordx4 v[2:3], off
	s_add_i32 m0, s59, 0x1c000
	v_lshl_add_u64 v[2:3], s[42:43], 0, v[0:1]
	global_load_lds_dwordx4 v[2:3], off
	v_lshl_add_u64 v[2:3], s[42:43], 0, v[130:131]
	s_add_i32 m0, s59, 0x1e000
	s_cmpk_lt_u32 s40, 0x100
	global_load_lds_dwordx4 v[2:3], off
	v_lshlrev_b32_e32 v2, 14, v15
	v_and_b32_e32 v2, 0xffff8000, v2
	v_lshl_add_u32 v2, v14, 11, v2
	v_and_b32_e32 v3, 1, v15
	v_lshl_or_b32 v2, v3, 6, v2
	v_lshl_add_u32 v136, v16, 1, v2
	v_lshlrev_b32_e32 v2, 14, v10
	v_and_b32_e32 v2, 0xffff8000, v2
	s_waitcnt vmcnt(8)
	s_barrier
	s_waitcnt vmcnt(6)
	v_lshl_add_u32 v2, v11, 11, v2
	v_and_b32_e32 v3, 1, v10
	v_lshl_or_b32 v2, v3, 6, v2
	v_readlane_b32 s42, v255, 24
	v_bitop3_b32 v146, v17, s41, v12 bitop3:0xde
	s_cselect_b64 s[40:41], -1, 0
	v_mov_b32_e32 v137, v1
	v_lshl_add_u32 v138, v13, 1, v2
	v_mov_b32_e32 v139, v1
	s_mov_b32 s75, 0
	v_add_u32_e32 v147, 0, v18
	v_readlane_b32 s77, v255, 14
	s_mov_b32 s76, s42
	s_mov_b32 s69, 0
	s_barrier
	v_readlane_b32 s43, v255, 25
	s_branch .LBB0_485

; #define PG8_STAGE(bufoff, gbase, voff) do { _Pragma("unroll") for (int _i = 0; _i < 2; ++_i) \
;         __builtin_amdgcn_global_load_lds((const unsigned*)((const char*)(gbase) + (voff)[_i]), (PG8_LAS unsigned*)(lds + (bufoff) + ldsw + _i * 8192), 16, 0, 0); } while (0)
; #define PG8_WAIT_V(n) asm volatile("s_waitcnt vmcnt(" #n ")" ::: "memory")
; #define PG8_BAR __builtin_amdgcn_s_barrier()
; template <class Epi, class Sched, bool ALIGN_EPI = false, bool SP2 = false>
; __device__ __forceinline__ void gemm_phase(PG8_LAS unsigned char* lds, const Gemm g, const Sched& S, const Epi& E, int tid_in) {
;     ...
;     const int aoff = lds_byte(wr * 64 + fr, fq * 8), boff = lds_byte(wc * 32 + fr, fq * 8);
;     ...
;         PG8_STAGE(PG8_SB(0, 0), cB, voffB); PG8_STAGE(PG8_SB(0, 1), cB + hstep, voffB); PG8_STAGE(PG8_SA(0, 0), cA, voffA); PG8_STAGE(PG8_SA(0, 1), cA + hstep, voffA);
;         if (wr == 1) PG8_BAR;
;         PG8_WAIT_V(2); PG8_BAR;
;         PG8_STAGE(PG8_SB(1, 0), cB + kstep, voffB); PG8_STAGE(PG8_SA(1, 0), cA + kstep, voffA); PG8_STAGE(PG8_SB(1, 1), cB + hstep + kstep, voffB);
;         PG8_WAIT_V(6); PG8_BAR;
.LBB0_557:
	s_add_u32 s28, s40, 0x3400000
	s_addc_u32 s29, s41, 0
	v_bfe_u32 v193, v10, 4, 2
	s_add_u32 s36, s40, 0x3000000
	v_and_b32_e32 v195, 15, v10
	v_lshlrev_b32_e32 v17, 4, v193
	v_lshlrev_b32_e32 v10, 2, v10
	s_addc_u32 s37, s41, 0
	s_and_b32 s65, s42, 3
	s_lshl_b32 s68, s39, 6
	v_lshl_or_b32 v17, v195, 6, v17
	s_lshl_b32 s39, s39, 13
	v_and_b32_e32 v10, 32, v10
	s_add_i32 m0, s61, 0x18000
	v_lshl_add_u64 v[8:9], v[8:9], 0, s[26:27]
	v_bitop3_b32 v18, v17, s39, v10 bitop3:0xde
	s_lshl_b32 s69, s65, 5
	s_lshl_b32 s39, s65, 12
	global_load_lds_dwordx4 v[8:9], off
	v_lshl_add_u64 v[6:7], v[6:7], 0, s[26:27]
	s_add_i32 m0, s61, 0x1a000
	s_add_i32 s75, s61, 0x8000
	s_add_i32 s76, s61, 0xa000
	global_load_lds_dwordx4 v[6:7], off
	v_lshl_add_u64 v[2:3], v[2:3], 0, s[26:27]
	s_mov_b32 m0, s75
	s_add_u32 s40, s52, 0x100080
	global_load_lds_dwordx4 v[2:3], off
	v_lshl_add_u64 v[2:3], v[4:5], 0, s[26:27]
	s_mov_b32 m0, s76
	s_addc_u32 s41, s53, 0
	global_load_lds_dwordx4 v[2:3], off
	s_add_i32 m0, s61, 0x1c000
	v_lshl_add_u64 v[2:3], s[40:41], 0, v[0:1]
	global_load_lds_dwordx4 v[2:3], off
	v_lshl_add_u64 v[2:3], s[40:41], 0, v[196:197]
	s_add_i32 m0, s61, 0x1e000
	s_cmpk_lt_u32 s38, 0x100
	global_load_lds_dwordx4 v[2:3], off
	v_lshlrev_b32_e32 v2, 16, v15
	v_and_b32_e32 v2, 0xfffe0000, v2
	v_lshl_add_u32 v2, v14, 13, v2
	v_and_b32_e32 v3, 1, v15
	v_lshl_or_b32 v2, v3, 6, v2
	v_lshl_add_u32 v202, v16, 1, v2
	v_lshlrev_b32_e32 v2, 16, v11
	v_and_b32_e32 v2, 0xfffe0000, v2
	s_waitcnt vmcnt(8)
	s_barrier
	s_waitcnt vmcnt(6)
	v_lshl_add_u32 v2, v12, 13, v2
	v_and_b32_e32 v3, 1, v11
	v_lshl_or_b32 v2, v3, 6, v2
	v_readlane_b32 s40, v254, 49
	v_bitop3_b32 v210, v17, s39, v10 bitop3:0xde
	s_cselect_b64 s[38:39], -1, 0
	v_mov_b32_e32 v203, v1
	v_lshl_add_u32 v204, v13, 1, v2
	v_mov_b32_e32 v205, v1
	s_mov_b32 s77, 0
	v_add_u32_e32 v211, 0, v18
	v_readlane_b32 s70, v254, 51
	s_mov_b32 s78, s40
	s_barrier
	v_readlane_b32 s41, v254, 50
	s_branch .LBB0_560
